# v2 plus: nt loads for x rows in the prologue rmsnorm
# speedup vs baseline: 1.0096x; 1.0096x over previous
.LBB0_64:
	v_readlane_b32 s0, v249, 4
	s_lshl_b32 s2, s0, 11
	v_readlane_b32 s0, v249, 3
	s_lshl_b32 s0, s0, 8
	v_readlane_b32 s1, v249, 0
	s_and_b32 s3, s0, 0x700
	s_and_b32 s0, s18, 0xffffffc0
	s_lshl_b32 s1, s1, 3
	s_add_i32 s4, s0, s1
	s_load_dwordx2 s[0:1], s[16:17], 0x0
	s_add_i32 s2, s4, s2
	s_add_i32 s2, s2, s3
	s_ashr_i32 s3, s2, 31
	s_lshl_b64 s[4:5], s[2:3], 12
	s_waitcnt lgkmcnt(0)
	s_add_u32 s0, s0, s4
	s_addc_u32 s1, s1, s5
	v_lshlrev_b32_e32 v106, 4, v108
	v_mov_b32_e32 v107, 0
	global_load_dwordx4 v[102:105], v106, s[0:1]
	global_load_dwordx4 v[98:101], v106, s[0:1] offset:1024
	global_load_dwordx4 v[94:97], v106, s[0:1] offset:2048
	global_load_dwordx4 v[78:81], v106, s[0:1] offset:3072
	v_lshl_add_u64 v[50:51], s[0:1], 0, v[106:107]
	s_movk_i32 s1, 0x2000
	v_add_co_u32_e32 v54, vcc, s1, v50
	s_movk_i32 s0, 0x1000
	s_nop 0
	v_addc_co_u32_e32 v55, vcc, 0, v51, vcc
	global_load_dwordx4 v[86:89], v[54:55], off offset:-4096
	v_add_co_u32_e32 v2, vcc, s0, v50
	s_movk_i32 s4, 0x3000
	s_nop 0
	v_addc_co_u32_e32 v3, vcc, 0, v51, vcc
	global_load_dwordx4 v[66:69], v[2:3], off offset:1024
	global_load_dwordx4 v[42:45], v[2:3], off offset:2048
	global_load_dwordx4 v[34:37], v[2:3], off offset:3072
	v_add_co_u32_e32 v56, vcc, s4, v50
	s_movk_i32 s5, 0x4000
	s_nop 0
	v_addc_co_u32_e32 v57, vcc, 0, v51, vcc
	v_add_co_u32_e32 v52, vcc, s5, v50
	s_movk_i32 s6, 0x7000
	s_nop 0
	v_addc_co_u32_e32 v53, vcc, 0, v51, vcc
	v_add_co_u32_e32 v110, vcc, s6, v50
	s_lshl_b64 s[0:1], s[2:3], 11
	s_nop 0
	v_addc_co_u32_e32 v111, vcc, 0, v51, vcc
	global_load_dwordx4 v[46:49], v[54:55], off
	global_load_dwordx4 v[38:41], v[54:55], off offset:1024
	global_load_dwordx4 v[30:33], v[54:55], off offset:2048
	global_load_dwordx4 v[26:29], v[54:55], off offset:3072
	global_load_dwordx4 v[18:21], v[56:57], off offset:1024
	global_load_dwordx4 v[14:17], v[56:57], off offset:2048
	global_load_dwordx4 v[10:13], v[56:57], off offset:3072
	global_load_dwordx4 v[22:25], v[52:53], off offset:-4096
	global_load_dwordx4 v[6:9], v[52:53], off
	global_load_dwordx4 v[2:5], v[110:111], off offset:3072
	s_movk_i32 s2, 0x5000
	global_load_dwordx4 v[74:77], v[52:53], off offset:1024
	global_load_dwordx4 v[62:65], v[52:53], off offset:2048
	s_add_u32 s0, s10, s0
	s_addc_u32 s1, s11, s1
	s_waitcnt vmcnt(19)
	v_mul_f32_e32 v1, v103, v103
	v_mul_f32_e32 v54, v105, v105
	s_waitcnt vmcnt(18)
	v_mul_f32_e32 v55, v99, v99
	v_mul_f32_e32 v56, v101, v101
	s_waitcnt vmcnt(17)
	v_mul_f32_e32 v57, v95, v95
	v_mul_f32_e32 v58, v97, v97
	s_waitcnt vmcnt(16)
	v_mul_f32_e32 v59, v79, v79
	v_mul_f32_e32 v60, v81, v81
	v_fmac_f32_e32 v1, v102, v102
	v_fmac_f32_e32 v54, v104, v104
	v_fmac_f32_e32 v55, v98, v98
	v_fmac_f32_e32 v56, v100, v100
	v_fmac_f32_e32 v57, v94, v94
	v_fmac_f32_e32 v58, v96, v96
	v_fmac_f32_e32 v59, v78, v78
	v_fmac_f32_e32 v60, v80, v80
	v_add_f32_e32 v1, v1, v54
	v_add_f32_e32 v54, v55, v56
	v_add_f32_e32 v55, v57, v58
	v_add_f32_e32 v56, v59, v60
	s_waitcnt vmcnt(15)
	v_mul_f32_e32 v57, v87, v87
	v_mul_f32_e32 v58, v89, v89
	s_waitcnt vmcnt(14)
	v_mul_f32_e32 v59, v67, v67
	v_mul_f32_e32 v60, v69, v69
	v_add_f32_e32 v1, v1, v54
	v_fmac_f32_e32 v57, v86, v86
	v_fmac_f32_e32 v58, v88, v88
	v_fmac_f32_e32 v59, v66, v66
	v_fmac_f32_e32 v60, v68, v68
	v_add_f32_e32 v1, v1, v55
	v_add_f32_e32 v54, v57, v58
	v_add_f32_e32 v55, v59, v60
	v_add_f32_e32 v1, v1, v56
	v_add_f32_e32 v54, v54, v55
	s_waitcnt vmcnt(13)
	v_mul_f32_e32 v55, v43, v43
	v_mul_f32_e32 v56, v45, v45
	v_fmac_f32_e32 v55, v42, v42
	v_fmac_f32_e32 v56, v44, v44
	v_add_f32_e32 v55, v55, v56
	v_mbcnt_lo_u32_b32 v56, -1, 0
	v_mbcnt_hi_u32_b32 v56, -1, v56
	v_and_b32_e32 v57, 64, v56
	v_add_u32_e32 v57, 64, v57
	v_xor_b32_e32 v58, 1, v56
	v_cmp_lt_i32_e32 vcc, v58, v57
	v_add_f32_e32 v54, v54, v55
	s_waitcnt vmcnt(12)
	v_mul_f32_e32 v55, v35, v35
	v_cndmask_b32_e32 v58, v56, v58, vcc
	v_lshlrev_b32_e32 v113, 2, v58
	ds_bpermute_b32 v58, v113, v1
	v_mul_f32_e32 v59, v37, v37
	v_fmac_f32_e32 v55, v34, v34
	v_fmac_f32_e32 v59, v36, v36
	v_add_f32_e32 v55, v55, v59
	s_waitcnt lgkmcnt(0)
	v_add_f32_e32 v1, v1, v58
	v_xor_b32_e32 v58, 2, v56
	v_cmp_lt_i32_e32 vcc, v58, v57
	v_add_f32_e32 v54, v54, v55
	ds_bpermute_b32 v55, v113, v54
	v_cndmask_b32_e32 v58, v56, v58, vcc
	v_lshlrev_b32_e32 v120, 2, v58
	ds_bpermute_b32 v58, v120, v1
	s_waitcnt lgkmcnt(1)
	v_add_f32_e32 v54, v54, v55
	ds_bpermute_b32 v55, v120, v54
	s_waitcnt lgkmcnt(1)
	v_add_f32_e32 v1, v1, v58
	v_xor_b32_e32 v58, 4, v56
	v_cmp_lt_i32_e32 vcc, v58, v57
	s_waitcnt lgkmcnt(0)
	v_add_f32_e32 v54, v54, v55
	v_cndmask_b32_e32 v58, v56, v58, vcc
	v_lshlrev_b32_e32 v121, 2, v58
	ds_bpermute_b32 v58, v121, v1
	v_add_co_u32_e32 v114, vcc, s2, v50
	ds_bpermute_b32 v55, v121, v54
	s_nop 0
	v_addc_co_u32_e32 v115, vcc, 0, v51, vcc
	s_waitcnt lgkmcnt(1)
	v_add_f32_e32 v1, v1, v58
	v_xor_b32_e32 v58, 8, v56
	v_cmp_lt_i32_e32 vcc, v58, v57
	s_movk_i32 s2, 0x6000
	s_nop 0
	v_cndmask_b32_e32 v58, v56, v58, vcc
	v_lshlrev_b32_e32 v122, 2, v58
	ds_bpermute_b32 v58, v122, v1
	v_add_co_u32_e32 v116, vcc, s2, v50
	s_waitcnt lgkmcnt(1)
	v_add_f32_e32 v50, v54, v55
	v_addc_co_u32_e32 v117, vcc, 0, v51, vcc
	s_waitcnt lgkmcnt(0)
	v_add_f32_e32 v51, v1, v58
	v_xor_b32_e32 v1, 16, v56
	ds_bpermute_b32 v54, v122, v50
	v_cmp_lt_i32_e32 vcc, v1, v57
	global_load_dwordx4 v[90:93], v[52:53], off offset:3072 nt
	global_load_dwordx4 v[82:85], v[116:117], off offset:-4096 nt
	global_load_dwordx4 v[70:73], v[114:115], off offset:1024 nt
	global_load_dwordx4 v[58:61], v[114:115], off offset:2048 nt
	v_cndmask_b32_e32 v1, v56, v1, vcc
	v_lshlrev_b32_e32 v1, 2, v1
	ds_bpermute_b32 v55, v1, v51
	s_waitcnt lgkmcnt(1)
	v_add_f32_e32 v106, v50, v54
	v_xor_b32_e32 v50, 32, v56
	v_cmp_lt_i32_e32 vcc, v50, v57
	ds_bpermute_b32 v112, v1, v106
	s_waitcnt lgkmcnt(1)
	v_add_f32_e32 v109, v51, v55
	v_cndmask_b32_e32 v50, v56, v50, vcc
	v_lshlrev_b32_e32 v233, 2, v50
	ds_bpermute_b32 v118, v233, v109
	s_waitcnt lgkmcnt(1)
	v_add_f32_e32 v106, v106, v112
	v_mov_b32_e32 v112, 0x358637bd
	ds_bpermute_b32 v119, v233, v106
	global_load_dwordx4 v[54:57], v[116:117], off nt
	global_load_dwordx4 v[50:53], v[116:117], off offset:1024 nt
	s_waitcnt lgkmcnt(1)
	v_add_f32_e32 v109, v109, v118
	v_fmamk_f32 v109, v109, 0x3a800000, v112
	v_rsq_f32_e32 v123, v109
	s_waitcnt lgkmcnt(0)
	v_add_f32_e32 v124, v106, v119
	v_lshlrev_b32_e32 v106, 3, v108
	v_lshl_add_u64 v[106:107], s[0:1], 0, v[106:107]
	v_mul_f32_e32 v102, v102, v123
	v_mul_f32_e32 v103, v103, v123
	v_bfe_u32 v108, v102, 16, 1
	s_movk_i32 s0, 0x7fff
	v_add3_u32 v102, v102, v108, s0
	v_bfe_u32 v108, v103, 16, 1
	v_lshrrev_b32_e32 v102, 16, v102
	v_add3_u32 v103, v103, v108, s0
	s_mov_b32 s1, 0xffff0000
	v_mul_f32_e32 v133, v78, v123
	v_fmamk_f32 v78, v124, 0x3a800000, v112
	v_and_or_b32 v118, v103, s1, v102
	v_mul_f32_e32 v102, v104, v123
	v_rsq_f32_e32 v124, v78
	v_mul_f32_e32 v103, v105, v123
	v_bfe_u32 v104, v102, 16, 1
	v_add3_u32 v102, v102, v104, s0
	v_bfe_u32 v104, v103, 16, 1
	v_lshrrev_b32_e32 v102, 16, v102
	v_add3_u32 v103, v103, v104, s0
	v_and_or_b32 v119, v103, s1, v102
	v_mul_f32_e32 v125, v98, v123
	v_mul_f32_e32 v126, v99, v123
	v_mul_f32_e32 v127, v100, v123
	v_mul_f32_e32 v128, v101, v123
	v_mul_f32_e32 v129, v94, v123
	v_mul_f32_e32 v130, v95, v123
	v_mul_f32_e32 v131, v96, v123
	v_mul_f32_e32 v132, v97, v123
	v_mul_f32_e32 v134, v79, v123
	v_mul_f32_e32 v135, v80, v123
	v_mul_f32_e32 v123, v81, v123
	v_mul_f32_e32 v136, v86, v124
	v_mul_f32_e32 v137, v87, v124
	v_mul_f32_e32 v138, v88, v124
	v_mul_f32_e32 v139, v89, v124
	v_mul_f32_e32 v140, v66, v124
	v_mul_f32_e32 v141, v67, v124
	v_mul_f32_e32 v142, v68, v124
	v_mul_f32_e32 v143, v69, v124
	global_load_dwordx4 v[98:101], v[116:117], off offset:2048 nt
	global_load_dwordx4 v[94:97], v[116:117], off offset:3072 nt
	global_load_dwordx4 v[102:105], v[114:115], off offset:3072 nt
	global_load_dwordx4 v[86:89], v[110:111], off nt
	global_load_dwordx4 v[78:81], v[110:111], off offset:1024 nt
	global_load_dwordx4 v[66:69], v[110:111], off offset:2048 nt
	v_bfe_u32 v110, v125, 16, 1
	v_add3_u32 v110, v125, v110, s0
	v_bfe_u32 v111, v126, 16, 1
	v_bfe_u32 v114, v127, 16, 1
	s_mov_b32 s2, 0x3001000
	v_add3_u32 v111, v126, v111, s0
	v_add3_u32 v115, v127, v114, s0
	v_bfe_u32 v114, v128, 16, 1
	v_lshrrev_b32_e32 v110, 16, v110
	v_add_co_u32_e32 v108, vcc, s2, v106
	v_add3_u32 v116, v128, v114, s0
	v_and_or_b32 v114, v111, s1, v110
	v_lshrrev_b32_e32 v110, 16, v115
	s_mov_b64 s[2:3], 0x3000000
	v_and_or_b32 v115, v116, s1, v110
	v_lshl_add_u64 v[110:111], v[106:107], 0, s[2:3]
	global_store_dwordx2 v[110:111], v[114:115], off offset:512
	v_bfe_u32 v114, v129, 16, 1
	v_add3_u32 v114, v129, v114, s0
	v_bfe_u32 v115, v130, 16, 1
	v_bfe_u32 v116, v131, 16, 1
	v_add3_u32 v115, v130, v115, s0
	v_add3_u32 v116, v131, v116, s0
	v_bfe_u32 v117, v132, 16, 1
	v_lshrrev_b32_e32 v114, 16, v114
	v_add3_u32 v117, v132, v117, s0
	v_and_or_b32 v114, v115, s1, v114
	v_lshrrev_b32_e32 v115, 16, v116
	v_and_or_b32 v115, v117, s1, v115
	global_store_dwordx2 v[110:111], v[114:115], off offset:1024
	v_bfe_u32 v114, v133, 16, 1
	v_add3_u32 v114, v133, v114, s0
	v_bfe_u32 v115, v134, 16, 1
	v_bfe_u32 v116, v135, 16, 1
	v_add3_u32 v115, v134, v115, s0
	v_add3_u32 v116, v135, v116, s0
	v_bfe_u32 v117, v123, 16, 1
	v_lshrrev_b32_e32 v114, 16, v114
	v_add3_u32 v117, v123, v117, s0
	v_and_or_b32 v114, v115, s1, v114
	v_lshrrev_b32_e32 v115, 16, v116
	v_and_or_b32 v115, v117, s1, v115
	global_store_dwordx2 v[110:111], v[114:115], off offset:1536
	v_bfe_u32 v114, v136, 16, 1
	v_add3_u32 v114, v136, v114, s0
	v_bfe_u32 v115, v137, 16, 1
	v_bfe_u32 v116, v138, 16, 1
	v_add3_u32 v115, v137, v115, s0
	v_add3_u32 v116, v138, v116, s0
	v_bfe_u32 v117, v139, 16, 1
	v_lshrrev_b32_e32 v114, 16, v114
	v_add3_u32 v117, v139, v117, s0
	v_and_or_b32 v114, v115, s1, v114
	v_lshrrev_b32_e32 v115, 16, v116
	v_and_or_b32 v115, v117, s1, v115
	global_store_dwordx2 v[110:111], v[114:115], off offset:2048
	s_waitcnt vmcnt(27)
	v_mul_f32_e32 v114, v47, v47
	v_mul_f32_e32 v115, v49, v49
	v_fmac_f32_e32 v114, v46, v46
	v_fmac_f32_e32 v115, v48, v48
	v_add_f32_e32 v114, v114, v115
	s_waitcnt vmcnt(26)
	v_mul_f32_e32 v115, v39, v39
	v_mul_f32_e32 v116, v41, v41
	v_fmac_f32_e32 v115, v38, v38
	v_fmac_f32_e32 v116, v40, v40
	v_add_f32_e32 v115, v115, v116
	v_add_f32_e32 v114, v114, v115
	s_waitcnt vmcnt(25)
	v_mul_f32_e32 v115, v31, v31
	v_mul_f32_e32 v116, v33, v33
	v_fmac_f32_e32 v115, v30, v30
	v_fmac_f32_e32 v116, v32, v32
	v_add_f32_e32 v115, v115, v116
	v_add_f32_e32 v114, v114, v115
	s_waitcnt vmcnt(24)
	v_mul_f32_e32 v115, v27, v27
	v_mul_f32_e32 v116, v29, v29
	v_fmac_f32_e32 v115, v26, v26
	v_fmac_f32_e32 v116, v28, v28
	v_add_f32_e32 v115, v115, v116
	v_add_f32_e32 v114, v114, v115
	s_waitcnt vmcnt(20)
	v_mul_f32_e32 v115, v23, v23
	v_mul_f32_e32 v116, v25, v25
	v_fmac_f32_e32 v115, v22, v22
	v_fmac_f32_e32 v116, v24, v24
	v_add_f32_e32 v115, v115, v116
	v_mul_f32_e32 v116, v19, v19
	v_mul_f32_e32 v117, v21, v21
	v_fmac_f32_e32 v116, v18, v18
	v_fmac_f32_e32 v117, v20, v20
	v_add_f32_e32 v116, v116, v117
	v_add_f32_e32 v115, v115, v116
	v_mul_f32_e32 v116, v15, v15
	v_mul_f32_e32 v117, v17, v17
	v_fmac_f32_e32 v116, v14, v14
	v_fmac_f32_e32 v117, v16, v16
	v_add_f32_e32 v116, v116, v117
	v_add_f32_e32 v115, v115, v116
	v_mul_f32_e32 v116, v11, v11
	v_mul_f32_e32 v117, v13, v13
	v_fmac_f32_e32 v116, v10, v10
	v_fmac_f32_e32 v117, v12, v12
	v_add_f32_e32 v116, v116, v117
	v_add_f32_e32 v115, v115, v116
	s_waitcnt vmcnt(19)
	v_mul_f32_e32 v116, v7, v7
	v_mul_f32_e32 v117, v9, v9
	v_addc_co_u32_e32 v109, vcc, 0, v107, vcc
	v_fmac_f32_e32 v116, v6, v6
	v_fmac_f32_e32 v117, v8, v8
	global_store_dwordx2 v[108:109], v[118:119], off offset:-4096
	v_add_f32_e32 v116, v116, v117
	s_waitcnt vmcnt(18)
	v_mul_f32_e32 v117, v75, v75
	v_mul_f32_e32 v118, v77, v77
	v_fmac_f32_e32 v117, v74, v74
	v_fmac_f32_e32 v118, v76, v76
	v_add_f32_e32 v117, v117, v118
	v_add_f32_e32 v116, v116, v117
	s_waitcnt vmcnt(17)
	v_mul_f32_e32 v117, v63, v63
	v_mul_f32_e32 v118, v65, v65
	v_fmac_f32_e32 v117, v62, v62
	v_fmac_f32_e32 v118, v64, v64
	v_add_f32_e32 v117, v117, v118
	v_add_f32_e32 v116, v116, v117
	s_waitcnt vmcnt(16)
	v_mul_f32_e32 v117, v91, v91
	v_mul_f32_e32 v118, v93, v93
	v_fmac_f32_e32 v117, v90, v90
	v_fmac_f32_e32 v118, v92, v92
	v_add_f32_e32 v117, v117, v118
	v_add_f32_e32 v116, v116, v117
	s_waitcnt vmcnt(15)
	v_mul_f32_e32 v117, v83, v83
	v_mul_f32_e32 v118, v85, v85
	v_fmac_f32_e32 v117, v82, v82
	v_fmac_f32_e32 v118, v84, v84
	v_add_f32_e32 v117, v117, v118
	s_waitcnt vmcnt(14)
	v_mul_f32_e32 v118, v71, v71
	v_mul_f32_e32 v119, v73, v73
	v_fmac_f32_e32 v118, v70, v70
	v_fmac_f32_e32 v119, v72, v72
	v_add_f32_e32 v118, v118, v119
	v_add_f32_e32 v117, v117, v118
	s_waitcnt vmcnt(13)
	v_mul_f32_e32 v118, v59, v59
	v_mul_f32_e32 v119, v61, v61
	v_fmac_f32_e32 v118, v58, v58
	v_fmac_f32_e32 v119, v60, v60
	v_add_f32_e32 v118, v118, v119
	v_add_f32_e32 v117, v117, v118
	s_waitcnt vmcnt(8)
	v_mul_f32_e32 v118, v103, v103
	v_mul_f32_e32 v119, v105, v105
	v_fmac_f32_e32 v118, v102, v102
	v_fmac_f32_e32 v119, v104, v104
	v_add_f32_e32 v118, v118, v119
	v_add_f32_e32 v117, v117, v118
	v_mul_f32_e32 v118, v55, v55
	v_mul_f32_e32 v119, v57, v57
	v_fmac_f32_e32 v118, v54, v54
	v_fmac_f32_e32 v119, v56, v56
	v_add_f32_e32 v118, v118, v119
	v_mul_f32_e32 v119, v51, v51
	v_mul_f32_e32 v123, v53, v53
	v_fmac_f32_e32 v119, v50, v50
	v_fmac_f32_e32 v123, v52, v52
	v_add_f32_e32 v119, v119, v123
	v_add_f32_e32 v118, v118, v119
	v_mul_f32_e32 v119, v99, v99
	v_mul_f32_e32 v123, v101, v101
	v_fmac_f32_e32 v119, v98, v98
	v_fmac_f32_e32 v123, v100, v100
	v_add_f32_e32 v119, v119, v123
	v_add_f32_e32 v118, v118, v119
	v_mul_f32_e32 v119, v95, v95
	v_mul_f32_e32 v123, v97, v97
	v_fmac_f32_e32 v119, v94, v94
	v_fmac_f32_e32 v123, v96, v96
	v_add_f32_e32 v119, v119, v123
	v_add_f32_e32 v118, v118, v119
	s_waitcnt vmcnt(7)
	v_mul_f32_e32 v119, v87, v87
	v_mul_f32_e32 v123, v89, v89
	v_fmac_f32_e32 v119, v86, v86
	v_fmac_f32_e32 v123, v88, v88
	v_add_f32_e32 v119, v119, v123
	s_waitcnt vmcnt(6)
	v_mul_f32_e32 v123, v79, v79
	v_mul_f32_e32 v125, v81, v81
	v_fmac_f32_e32 v123, v78, v78
	v_fmac_f32_e32 v125, v80, v80
	v_add_f32_e32 v123, v123, v125
	v_add_f32_e32 v119, v119, v123
	s_waitcnt vmcnt(5)
	v_mul_f32_e32 v123, v67, v67
	v_mul_f32_e32 v125, v69, v69
	v_fmac_f32_e32 v123, v66, v66
	v_fmac_f32_e32 v125, v68, v68
	v_add_f32_e32 v123, v123, v125
	ds_bpermute_b32 v125, v113, v114
	v_add_f32_e32 v119, v119, v123
	v_mul_f32_e32 v123, v3, v3
	v_mul_f32_e32 v126, v5, v5
	v_fmac_f32_e32 v123, v2, v2
	v_fmac_f32_e32 v126, v4, v4
	v_add_f32_e32 v123, v123, v126
	v_add_f32_e32 v119, v119, v123
	s_waitcnt lgkmcnt(0)
	v_add_f32_e32 v114, v114, v125
	ds_bpermute_b32 v123, v113, v115
	ds_bpermute_b32 v125, v113, v116
	ds_bpermute_b32 v126, v113, v117
	ds_bpermute_b32 v127, v113, v118
	ds_bpermute_b32 v113, v113, v119
	s_waitcnt lgkmcnt(4)
	v_add_f32_e32 v115, v115, v123
	ds_bpermute_b32 v123, v120, v115
	s_waitcnt lgkmcnt(4)
	v_add_f32_e32 v116, v116, v125
	s_waitcnt lgkmcnt(3)
	v_add_f32_e32 v117, v117, v126
	s_waitcnt lgkmcnt(1)
	v_add_f32_e32 v113, v119, v113
	ds_bpermute_b32 v119, v120, v114
	v_add_f32_e32 v118, v118, v127
	ds_bpermute_b32 v125, v120, v116
	ds_bpermute_b32 v126, v120, v117
	ds_bpermute_b32 v127, v120, v118
	s_waitcnt lgkmcnt(3)
	v_add_f32_e32 v114, v114, v119
	v_add_f32_e32 v115, v115, v123
	ds_bpermute_b32 v119, v120, v113
	ds_bpermute_b32 v120, v121, v114
	ds_bpermute_b32 v123, v121, v115
	s_waitcnt lgkmcnt(5)
	v_add_f32_e32 v116, v116, v125
	s_waitcnt lgkmcnt(4)
	v_add_f32_e32 v117, v117, v126
	s_waitcnt lgkmcnt(3)
	v_add_f32_e32 v118, v118, v127
	s_waitcnt lgkmcnt(2)
	v_add_f32_e32 v113, v113, v119
	s_waitcnt lgkmcnt(1)
	v_add_f32_e32 v114, v114, v120
	ds_bpermute_b32 v125, v121, v116
	ds_bpermute_b32 v126, v121, v117
	s_waitcnt lgkmcnt(2)
	v_add_f32_e32 v115, v115, v123
	ds_bpermute_b32 v119, v121, v118
	ds_bpermute_b32 v120, v121, v113
	ds_bpermute_b32 v121, v122, v114
	ds_bpermute_b32 v123, v122, v115
	s_waitcnt lgkmcnt(5)
	v_add_f32_e32 v116, v116, v125
	s_waitcnt lgkmcnt(4)
	v_add_f32_e32 v117, v117, v126
	s_waitcnt lgkmcnt(3)
	v_add_f32_e32 v118, v118, v119
	s_waitcnt lgkmcnt(2)
	v_add_f32_e32 v113, v113, v120
	s_waitcnt lgkmcnt(1)
	v_add_f32_e32 v114, v114, v121
	ds_bpermute_b32 v125, v122, v116
	s_waitcnt lgkmcnt(1)
	v_add_f32_e32 v115, v115, v123
	ds_bpermute_b32 v119, v122, v117
	ds_bpermute_b32 v120, v122, v118
	ds_bpermute_b32 v121, v122, v113
	ds_bpermute_b32 v122, v1, v114
	ds_bpermute_b32 v123, v1, v115
	s_waitcnt lgkmcnt(5)
	v_add_f32_e32 v116, v116, v125
	s_waitcnt lgkmcnt(4)
	v_add_f32_e32 v117, v117, v119
	ds_bpermute_b32 v119, v1, v116
	s_waitcnt lgkmcnt(2)
	v_add_f32_e32 v114, v114, v122
	s_waitcnt lgkmcnt(1)
	v_add_f32_e32 v115, v115, v123
	ds_bpermute_b32 v123, v233, v114
	v_add_f32_e32 v118, v118, v120
	ds_bpermute_b32 v120, v1, v117
	v_add_f32_e32 v113, v113, v121
	ds_bpermute_b32 v121, v1, v118
	s_waitcnt lgkmcnt(3)
	v_add_f32_e32 v116, v116, v119
	s_waitcnt lgkmcnt(2)
	v_add_f32_e32 v119, v114, v123
	ds_bpermute_b32 v114, v233, v115
	s_waitcnt lgkmcnt(2)
	v_add_f32_e32 v117, v117, v120
	ds_bpermute_b32 v120, v233, v116
	s_waitcnt lgkmcnt(2)
	v_add_f32_e32 v118, v118, v121
	ds_bpermute_b32 v121, v233, v117
	s_waitcnt lgkmcnt(2)
	v_add_f32_e32 v125, v115, v114
	v_bfe_u32 v114, v140, 16, 1
	s_waitcnt lgkmcnt(1)
	v_add_f32_e32 v116, v116, v120
	v_add3_u32 v114, v140, v114, s0
	v_bfe_u32 v115, v141, 16, 1
	v_bfe_u32 v120, v142, 16, 1
	s_waitcnt lgkmcnt(0)
	v_add_f32_e32 v117, v117, v121
	v_add3_u32 v115, v141, v115, s0
	v_add3_u32 v120, v142, v120, s0
	v_bfe_u32 v121, v143, 16, 1
	v_lshrrev_b32_e32 v114, 16, v114
	v_add3_u32 v121, v143, v121, s0
	v_and_or_b32 v114, v115, s1, v114
	v_lshrrev_b32_e32 v115, 16, v120
	v_and_or_b32 v115, v121, s1, v115
	v_mul_f32_e32 v42, v42, v124
	global_store_dwordx2 v[110:111], v[114:115], off offset:2560
	v_mul_f32_e32 v43, v43, v124
	v_bfe_u32 v114, v42, 16, 1
	v_add3_u32 v42, v42, v114, s0
	v_bfe_u32 v114, v43, 16, 1
	v_lshrrev_b32_e32 v42, 16, v42
	v_add3_u32 v43, v43, v114, s0
	v_and_or_b32 v42, v43, s1, v42
	v_mul_f32_e32 v43, v44, v124
	v_mul_f32_e32 v44, v45, v124
	v_bfe_u32 v45, v43, 16, 1
	v_add3_u32 v43, v43, v45, s0
	v_bfe_u32 v45, v44, 16, 1
	v_lshrrev_b32_e32 v43, 16, v43
	v_add3_u32 v44, v44, v45, s0
	v_and_or_b32 v43, v44, s1, v43
	v_mul_f32_e32 v34, v34, v124
	global_store_dwordx2 v[110:111], v[42:43], off offset:3072
	v_mul_f32_e32 v35, v35, v124
	v_bfe_u32 v42, v34, 16, 1
	v_add3_u32 v34, v34, v42, s0
	v_bfe_u32 v42, v35, 16, 1
	v_lshrrev_b32_e32 v34, 16, v34
	v_add3_u32 v35, v35, v42, s0
	v_and_or_b32 v34, v35, s1, v34
	v_mul_f32_e32 v35, v36, v124
	v_fmamk_f32 v42, v119, 0x3a800000, v112
	v_mul_f32_e32 v36, v37, v124
	v_bfe_u32 v37, v35, 16, 1
	v_rsq_f32_e32 v42, v42
	v_add3_u32 v35, v35, v37, s0
	v_bfe_u32 v37, v36, 16, 1
	v_lshrrev_b32_e32 v35, 16, v35
	v_add3_u32 v36, v36, v37, s0
	v_and_or_b32 v35, v36, s1, v35
	global_store_dwordx2 v[110:111], v[34:35], off offset:3584
	v_mul_f32_e32 v34, v46, v42
	v_mul_f32_e32 v35, v47, v42
	v_bfe_u32 v36, v34, 16, 1
	v_add3_u32 v34, v34, v36, s0
	v_bfe_u32 v36, v35, 16, 1
	v_lshrrev_b32_e32 v34, 16, v34
	v_add3_u32 v35, v35, v36, s0
	v_and_or_b32 v34, v35, s1, v34
	v_mul_f32_e32 v35, v48, v42
	v_mul_f32_e32 v36, v49, v42
	v_bfe_u32 v37, v35, 16, 1
	v_add3_u32 v35, v35, v37, s0
	v_bfe_u32 v37, v36, 16, 1
	v_lshrrev_b32_e32 v35, 16, v35
	v_add3_u32 v36, v36, v37, s0
	v_and_or_b32 v35, v36, s1, v35
	global_store_dwordx2 v[108:109], v[34:35], off
	v_mul_f32_e32 v34, v38, v42
	v_mul_f32_e32 v35, v39, v42
	v_bfe_u32 v36, v34, 16, 1
	v_add3_u32 v34, v34, v36, s0
	v_bfe_u32 v36, v35, 16, 1
	v_lshrrev_b32_e32 v34, 16, v34
	v_add3_u32 v35, v35, v36, s0
	v_and_or_b32 v34, v35, s1, v34
	v_mul_f32_e32 v35, v40, v42
	v_mul_f32_e32 v36, v41, v42
	v_bfe_u32 v37, v35, 16, 1
	v_add3_u32 v35, v35, v37, s0
	v_bfe_u32 v37, v36, 16, 1
	v_lshrrev_b32_e32 v35, 16, v35
	v_add3_u32 v36, v36, v37, s0
	v_and_or_b32 v35, v36, s1, v35
	v_mul_f32_e32 v30, v30, v42
	global_store_dwordx2 v[108:109], v[34:35], off offset:512
	v_mul_f32_e32 v31, v31, v42
	v_bfe_u32 v34, v30, 16, 1
	v_add3_u32 v30, v30, v34, s0
	v_bfe_u32 v34, v31, 16, 1
	v_lshrrev_b32_e32 v30, 16, v30
	v_add3_u32 v31, v31, v34, s0
	v_and_or_b32 v30, v31, s1, v30
	v_mul_f32_e32 v31, v32, v42
	v_mul_f32_e32 v32, v33, v42
	v_bfe_u32 v33, v31, 16, 1
	v_add3_u32 v31, v31, v33, s0
	v_bfe_u32 v33, v32, 16, 1
	v_lshrrev_b32_e32 v31, 16, v31
	v_add3_u32 v32, v32, v33, s0
	v_and_or_b32 v31, v32, s1, v31
	v_mul_f32_e32 v26, v26, v42
	global_store_dwordx2 v[108:109], v[30:31], off offset:1024
	v_mul_f32_e32 v27, v27, v42
	v_bfe_u32 v30, v26, 16, 1
	v_add3_u32 v26, v26, v30, s0
	v_bfe_u32 v30, v27, 16, 1
	v_lshrrev_b32_e32 v26, 16, v26
	v_add3_u32 v27, v27, v30, s0
	v_fmamk_f32 v30, v125, 0x3a800000, v112
	v_and_or_b32 v26, v27, s1, v26
	v_mul_f32_e32 v27, v28, v42
	v_rsq_f32_e32 v30, v30
	v_mul_f32_e32 v28, v29, v42
	v_bfe_u32 v29, v27, 16, 1
	v_add3_u32 v27, v27, v29, s0
	v_bfe_u32 v29, v28, 16, 1
	v_lshrrev_b32_e32 v27, 16, v27
	v_add3_u32 v28, v28, v29, s0
	v_and_or_b32 v27, v28, s1, v27
	v_mul_f32_e32 v22, v22, v30
	global_store_dwordx2 v[108:109], v[26:27], off offset:1536
	v_mul_f32_e32 v23, v23, v30
	v_bfe_u32 v26, v22, 16, 1
	v_add3_u32 v22, v22, v26, s0
	v_bfe_u32 v26, v23, 16, 1
	v_lshrrev_b32_e32 v22, 16, v22
	v_add3_u32 v23, v23, v26, s0
	v_and_or_b32 v22, v23, s1, v22
	v_mul_f32_e32 v23, v24, v30
	v_mul_f32_e32 v24, v25, v30
	v_bfe_u32 v25, v23, 16, 1
	v_add3_u32 v23, v23, v25, s0
	v_bfe_u32 v25, v24, 16, 1
	v_lshrrev_b32_e32 v23, 16, v23
	v_add3_u32 v24, v24, v25, s0
	v_and_or_b32 v23, v24, s1, v23
	v_mul_f32_e32 v18, v18, v30
	global_store_dwordx2 v[108:109], v[22:23], off offset:2048
	v_mul_f32_e32 v19, v19, v30
	v_bfe_u32 v22, v18, 16, 1
	v_add3_u32 v18, v18, v22, s0
	v_bfe_u32 v22, v19, 16, 1
	v_lshrrev_b32_e32 v18, 16, v18
	v_add3_u32 v19, v19, v22, s0
	v_and_or_b32 v18, v19, s1, v18
	v_mul_f32_e32 v19, v20, v30
	v_mul_f32_e32 v20, v21, v30
	v_bfe_u32 v21, v19, 16, 1
	v_add3_u32 v19, v19, v21, s0
	v_bfe_u32 v21, v20, 16, 1
	v_lshrrev_b32_e32 v19, 16, v19
	v_add3_u32 v20, v20, v21, s0
	v_and_or_b32 v19, v20, s1, v19
	v_mul_f32_e32 v14, v14, v30
	global_store_dwordx2 v[108:109], v[18:19], off offset:2560
	v_mul_f32_e32 v15, v15, v30
	v_bfe_u32 v18, v14, 16, 1
	v_add3_u32 v14, v14, v18, s0
	v_bfe_u32 v18, v15, 16, 1
	v_lshrrev_b32_e32 v14, 16, v14
	v_add3_u32 v15, v15, v18, s0
	v_and_or_b32 v14, v15, s1, v14
	v_mul_f32_e32 v15, v16, v30
	v_mul_f32_e32 v16, v17, v30
	v_bfe_u32 v17, v15, 16, 1
	v_add3_u32 v15, v15, v17, s0
	v_bfe_u32 v17, v16, 16, 1
	v_lshrrev_b32_e32 v15, 16, v15
	v_add3_u32 v16, v16, v17, s0
	v_and_or_b32 v15, v16, s1, v15
	v_mul_f32_e32 v10, v10, v30
	global_store_dwordx2 v[108:109], v[14:15], off offset:3072
	v_mul_f32_e32 v11, v11, v30
	v_bfe_u32 v14, v10, 16, 1
	v_add3_u32 v10, v10, v14, s0
	v_bfe_u32 v14, v11, 16, 1
	v_lshrrev_b32_e32 v10, 16, v10
	v_add3_u32 v11, v11, v14, s0
	v_fmamk_f32 v14, v116, 0x3a800000, v112
	v_and_or_b32 v10, v11, s1, v10
	v_mul_f32_e32 v11, v12, v30
	v_rsq_f32_e32 v14, v14
	v_mul_f32_e32 v12, v13, v30
	v_bfe_u32 v13, v11, 16, 1
	v_add3_u32 v11, v11, v13, s0
	v_bfe_u32 v13, v12, 16, 1
	v_lshrrev_b32_e32 v11, 16, v11
	v_add3_u32 v12, v12, v13, s0
	v_and_or_b32 v11, v12, s1, v11
	v_mul_f32_e32 v6, v6, v14
	global_store_dwordx2 v[108:109], v[10:11], off offset:3584
	v_mul_f32_e32 v7, v7, v14
	v_bfe_u32 v10, v6, 16, 1
	v_add3_u32 v6, v6, v10, s0
	v_bfe_u32 v10, v7, 16, 1
	v_lshrrev_b32_e32 v6, 16, v6
	v_add3_u32 v7, v7, v10, s0
	v_and_or_b32 v10, v7, s1, v6
	v_mul_f32_e32 v6, v8, v14
	v_mul_f32_e32 v7, v9, v14
	v_bfe_u32 v8, v6, 16, 1
	v_add3_u32 v6, v6, v8, s0
	v_bfe_u32 v8, v7, 16, 1
	s_mov_b32 s2, 0x3002000
	v_add3_u32 v7, v7, v8, s0
	v_add_co_u32_e32 v8, vcc, s2, v106
	v_lshrrev_b32_e32 v6, 16, v6
	s_nop 0
	v_addc_co_u32_e32 v9, vcc, 0, v107, vcc
	s_mov_b32 s2, 0x3003000
	v_and_or_b32 v11, v7, s1, v6
	v_add_co_u32_e32 v6, vcc, s2, v106
	ds_bpermute_b32 v122, v1, v113
	s_nop 0
	v_addc_co_u32_e32 v7, vcc, 0, v107, vcc
	global_store_dwordx2 v[6:7], v[10:11], off offset:-4096
	v_mul_f32_e32 v10, v74, v14
	v_mul_f32_e32 v11, v75, v14
	v_bfe_u32 v12, v10, 16, 1
	v_add3_u32 v10, v10, v12, s0
	v_bfe_u32 v12, v11, 16, 1
	v_lshrrev_b32_e32 v10, 16, v10
	v_add3_u32 v11, v11, v12, s0
	v_and_or_b32 v10, v11, s1, v10
	v_mul_f32_e32 v11, v76, v14
	v_mul_f32_e32 v12, v77, v14
	v_bfe_u32 v13, v11, 16, 1
	v_add3_u32 v11, v11, v13, s0
	v_bfe_u32 v13, v12, 16, 1
	v_lshrrev_b32_e32 v11, 16, v11
	v_add3_u32 v12, v12, v13, s0
	v_and_or_b32 v11, v12, s1, v11
	global_store_dwordx2 v[8:9], v[10:11], off offset:512
	v_mul_f32_e32 v10, v62, v14
	v_mul_f32_e32 v11, v63, v14
	v_bfe_u32 v12, v10, 16, 1
	v_add3_u32 v10, v10, v12, s0
	v_bfe_u32 v12, v11, 16, 1
	v_lshrrev_b32_e32 v10, 16, v10
	v_add3_u32 v11, v11, v12, s0
	v_and_or_b32 v10, v11, s1, v10
	v_mul_f32_e32 v11, v64, v14
	v_mul_f32_e32 v12, v65, v14
	v_bfe_u32 v13, v11, 16, 1
	v_add3_u32 v11, v11, v13, s0
	v_bfe_u32 v13, v12, 16, 1
	v_lshrrev_b32_e32 v11, 16, v11
	v_add3_u32 v12, v12, v13, s0
	v_and_or_b32 v11, v12, s1, v11
	global_store_dwordx2 v[8:9], v[10:11], off offset:1024
	v_mul_f32_e32 v10, v90, v14
	v_mul_f32_e32 v11, v91, v14
	v_bfe_u32 v12, v10, 16, 1
	v_add3_u32 v10, v10, v12, s0
	v_bfe_u32 v12, v11, 16, 1
	v_lshrrev_b32_e32 v10, 16, v10
	v_add3_u32 v11, v11, v12, s0
	v_and_or_b32 v10, v11, s1, v10
	v_mul_f32_e32 v11, v92, v14
	v_mul_f32_e32 v12, v93, v14
	v_fmamk_f32 v14, v117, 0x3a800000, v112
	v_bfe_u32 v13, v11, 16, 1
	v_rsq_f32_e32 v14, v14
	v_add3_u32 v11, v11, v13, s0
	v_bfe_u32 v13, v12, 16, 1
	v_lshrrev_b32_e32 v11, 16, v11
	v_add3_u32 v12, v12, v13, s0
	v_and_or_b32 v11, v12, s1, v11
	global_store_dwordx2 v[8:9], v[10:11], off offset:1536
	v_mul_f32_e32 v10, v82, v14
	v_mul_f32_e32 v11, v83, v14
	v_bfe_u32 v12, v10, 16, 1
	v_add3_u32 v10, v10, v12, s0
	v_bfe_u32 v12, v11, 16, 1
	v_lshrrev_b32_e32 v10, 16, v10
	v_add3_u32 v11, v11, v12, s0
	v_and_or_b32 v10, v11, s1, v10
	v_mul_f32_e32 v11, v84, v14
	v_mul_f32_e32 v12, v85, v14
	v_bfe_u32 v13, v11, 16, 1
	v_add3_u32 v11, v11, v13, s0
	v_bfe_u32 v13, v12, 16, 1
	v_lshrrev_b32_e32 v11, 16, v11
	v_add3_u32 v12, v12, v13, s0
	v_and_or_b32 v11, v12, s1, v11
	global_store_dwordx2 v[8:9], v[10:11], off offset:2048
	v_mul_f32_e32 v10, v70, v14
	v_mul_f32_e32 v11, v71, v14
	v_bfe_u32 v12, v10, 16, 1
	v_add3_u32 v10, v10, v12, s0
	v_bfe_u32 v12, v11, 16, 1
	v_lshrrev_b32_e32 v10, 16, v10
	v_add3_u32 v11, v11, v12, s0
	v_and_or_b32 v10, v11, s1, v10
	v_mul_f32_e32 v11, v72, v14
	v_mul_f32_e32 v12, v73, v14
	v_bfe_u32 v13, v11, 16, 1
	v_add3_u32 v11, v11, v13, s0
	v_bfe_u32 v13, v12, 16, 1
	v_lshrrev_b32_e32 v11, 16, v11
	v_add3_u32 v12, v12, v13, s0
	v_and_or_b32 v11, v12, s1, v11
	global_store_dwordx2 v[8:9], v[10:11], off offset:2560
	v_mul_f32_e32 v10, v58, v14
	v_mul_f32_e32 v11, v59, v14
	v_bfe_u32 v12, v10, 16, 1
	v_add3_u32 v10, v10, v12, s0
	v_bfe_u32 v12, v11, 16, 1
	v_lshrrev_b32_e32 v10, 16, v10
	v_add3_u32 v11, v11, v12, s0
	v_and_or_b32 v10, v11, s1, v10
	v_mul_f32_e32 v11, v60, v14
	v_mul_f32_e32 v12, v61, v14
	v_bfe_u32 v13, v11, 16, 1
	v_add3_u32 v11, v11, v13, s0
	v_bfe_u32 v13, v12, 16, 1
	s_waitcnt lgkmcnt(0)
	v_add_f32_e32 v113, v113, v122
	ds_bpermute_b32 v122, v233, v118
	v_lshrrev_b32_e32 v11, 16, v11
	v_add3_u32 v12, v12, v13, s0
	v_and_or_b32 v11, v12, s1, v11
	global_store_dwordx2 v[8:9], v[10:11], off offset:3072
	v_mul_f32_e32 v10, v102, v14
	v_mul_f32_e32 v11, v103, v14
	v_bfe_u32 v12, v10, 16, 1
	v_add3_u32 v10, v10, v12, s0
	v_bfe_u32 v12, v11, 16, 1
	s_waitcnt lgkmcnt(0)
	v_add_f32_e32 v118, v118, v122
	v_lshrrev_b32_e32 v10, 16, v10
	v_add3_u32 v11, v11, v12, s0
	v_and_or_b32 v10, v11, s1, v10
	v_mul_f32_e32 v11, v104, v14
	v_mul_f32_e32 v12, v105, v14
	v_fmamk_f32 v14, v118, 0x3a800000, v112
	v_bfe_u32 v13, v11, 16, 1
	v_rsq_f32_e32 v14, v14
	v_add3_u32 v11, v11, v13, s0
	v_bfe_u32 v13, v12, 16, 1
	v_lshrrev_b32_e32 v11, 16, v11
	v_add3_u32 v12, v12, v13, s0
	v_and_or_b32 v11, v12, s1, v11
	global_store_dwordx2 v[8:9], v[10:11], off offset:3584
	v_mul_f32_e32 v8, v54, v14
	v_mul_f32_e32 v9, v55, v14
	v_bfe_u32 v10, v8, 16, 1
	v_add3_u32 v8, v8, v10, s0
	v_bfe_u32 v10, v9, 16, 1
	v_lshrrev_b32_e32 v8, 16, v8
	v_add3_u32 v9, v9, v10, s0
	v_and_or_b32 v8, v9, s1, v8
	v_mul_f32_e32 v9, v56, v14
	v_mul_f32_e32 v10, v57, v14
	v_bfe_u32 v11, v9, 16, 1
	v_add3_u32 v9, v9, v11, s0
	v_bfe_u32 v11, v10, 16, 1
	v_lshrrev_b32_e32 v9, 16, v9
	v_add3_u32 v10, v10, v11, s0
	v_and_or_b32 v9, v10, s1, v9
	global_store_dwordx2 v[6:7], v[8:9], off
	v_mul_f32_e32 v8, v50, v14
	v_mul_f32_e32 v9, v51, v14
	v_bfe_u32 v10, v8, 16, 1
	v_add3_u32 v8, v8, v10, s0
	v_bfe_u32 v10, v9, 16, 1
	v_lshrrev_b32_e32 v8, 16, v8
	v_add3_u32 v9, v9, v10, s0
	v_and_or_b32 v8, v9, s1, v8
	v_mul_f32_e32 v9, v52, v14
	v_mul_f32_e32 v10, v53, v14
	v_bfe_u32 v11, v9, 16, 1
	v_add3_u32 v9, v9, v11, s0
	v_bfe_u32 v11, v10, 16, 1
	v_lshrrev_b32_e32 v9, 16, v9
	v_add3_u32 v10, v10, v11, s0
	v_and_or_b32 v9, v10, s1, v9
	global_store_dwordx2 v[6:7], v[8:9], off offset:512
	v_mul_f32_e32 v8, v98, v14
	v_mul_f32_e32 v9, v99, v14
	v_bfe_u32 v10, v8, 16, 1
	v_add3_u32 v8, v8, v10, s0
	v_bfe_u32 v10, v9, 16, 1
	v_lshrrev_b32_e32 v8, 16, v8
	v_add3_u32 v9, v9, v10, s0
	v_and_or_b32 v8, v9, s1, v8
	v_mul_f32_e32 v9, v100, v14
	v_mul_f32_e32 v10, v101, v14
	v_bfe_u32 v11, v9, 16, 1
	v_add3_u32 v9, v9, v11, s0
	v_bfe_u32 v11, v10, 16, 1
	ds_bpermute_b32 v123, v233, v113
	v_lshrrev_b32_e32 v9, 16, v9
	v_add3_u32 v10, v10, v11, s0
	v_and_or_b32 v9, v10, s1, v9
	global_store_dwordx2 v[6:7], v[8:9], off offset:1024
	v_mul_f32_e32 v8, v94, v14
	v_mul_f32_e32 v9, v95, v14
	v_bfe_u32 v10, v8, 16, 1
	v_add3_u32 v8, v8, v10, s0
	v_bfe_u32 v10, v9, 16, 1
	s_waitcnt lgkmcnt(0)
	v_add_f32_e32 v113, v113, v123
	v_lshrrev_b32_e32 v8, 16, v8
	v_add3_u32 v9, v9, v10, s0
	v_and_or_b32 v8, v9, s1, v8
	v_mul_f32_e32 v9, v96, v14
	v_fmac_f32_e32 v112, 0x3a800000, v113
	v_mul_f32_e32 v10, v97, v14
	v_bfe_u32 v11, v9, 16, 1
	v_rsq_f32_e32 v12, v112
	v_add3_u32 v9, v9, v11, s0
	v_bfe_u32 v11, v10, 16, 1
	v_lshrrev_b32_e32 v9, 16, v9
	v_add3_u32 v10, v10, v11, s0
	v_and_or_b32 v9, v10, s1, v9
	global_store_dwordx2 v[6:7], v[8:9], off offset:1536
	v_mul_f32_e32 v8, v86, v12
	v_mul_f32_e32 v9, v87, v12
	v_bfe_u32 v10, v8, 16, 1
	v_add3_u32 v8, v8, v10, s0
	v_bfe_u32 v10, v9, 16, 1
	v_lshrrev_b32_e32 v8, 16, v8
	v_add3_u32 v9, v9, v10, s0
	v_and_or_b32 v8, v9, s1, v8
	v_mul_f32_e32 v9, v88, v12
	v_mul_f32_e32 v10, v89, v12
	v_bfe_u32 v11, v9, 16, 1
	v_add3_u32 v9, v9, v11, s0
	v_bfe_u32 v11, v10, 16, 1
	v_lshrrev_b32_e32 v9, 16, v9
	v_add3_u32 v10, v10, v11, s0
	v_and_or_b32 v9, v10, s1, v9
	global_store_dwordx2 v[6:7], v[8:9], off offset:2048
	v_mul_f32_e32 v8, v78, v12
	v_mul_f32_e32 v9, v79, v12
	v_bfe_u32 v10, v8, 16, 1
	v_add3_u32 v8, v8, v10, s0
	v_bfe_u32 v10, v9, 16, 1
	v_lshrrev_b32_e32 v8, 16, v8
	v_add3_u32 v9, v9, v10, s0
	v_and_or_b32 v8, v9, s1, v8
	v_mul_f32_e32 v9, v80, v12
	v_mul_f32_e32 v10, v81, v12
	v_bfe_u32 v11, v9, 16, 1
	v_add3_u32 v9, v9, v11, s0
	v_bfe_u32 v11, v10, 16, 1
	v_lshrrev_b32_e32 v9, 16, v9
	v_add3_u32 v10, v10, v11, s0
	v_and_or_b32 v9, v10, s1, v9
	global_store_dwordx2 v[6:7], v[8:9], off offset:2560
	v_mul_f32_e32 v8, v66, v12
	v_mul_f32_e32 v9, v67, v12
	v_bfe_u32 v10, v8, 16, 1
	v_add3_u32 v8, v8, v10, s0
	v_bfe_u32 v10, v9, 16, 1
	v_lshrrev_b32_e32 v8, 16, v8
	v_add3_u32 v9, v9, v10, s0
	v_and_or_b32 v8, v9, s1, v8
	v_mul_f32_e32 v9, v68, v12
	v_mul_f32_e32 v10, v69, v12
	v_bfe_u32 v11, v9, 16, 1
	v_add3_u32 v9, v9, v11, s0
	v_bfe_u32 v11, v10, 16, 1
	v_lshrrev_b32_e32 v9, 16, v9
	v_add3_u32 v10, v10, v11, s0
	v_and_or_b32 v9, v10, s1, v9
	v_mul_f32_e32 v2, v2, v12
	global_store_dwordx2 v[6:7], v[8:9], off offset:3072
	v_mul_f32_e32 v3, v3, v12
	v_bfe_u32 v8, v2, 16, 1
	v_add3_u32 v2, v2, v8, s0
	v_bfe_u32 v8, v3, 16, 1
	v_lshrrev_b32_e32 v2, 16, v2
	v_add3_u32 v3, v3, v8, s0
	v_and_or_b32 v2, v3, s1, v2
	v_mul_f32_e32 v3, v4, v12
	v_mul_f32_e32 v4, v5, v12
	v_bfe_u32 v5, v3, 16, 1
	v_add3_u32 v3, v3, v5, s0
	v_bfe_u32 v5, v4, 16, 1
	v_lshrrev_b32_e32 v3, 16, v3
	v_add3_u32 v4, v4, v5, s0
	v_and_or_b32 v3, v4, s1, v3
	global_store_dwordx2 v[6:7], v[2:3], off offset:3584
	s_waitcnt vmcnt(0)
	s_barrier
	s_and_saveexec_b64 s[0:1], s[68:69]
	s_cbranch_execz .LBB0_67
	s_mov_b64 s[2:3], exec
	v_mbcnt_lo_u32_b32 v2, s2, 0
	v_mbcnt_hi_u32_b32 v2, s3, v2
	v_cmp_eq_u32_e32 vcc, 0, v2
	s_and_b64 s[4:5], exec, vcc
	s_mov_b64 exec, s[4:5]
	s_cbranch_execz .LBB0_67
	s_bcnt1_i32_b64 s2, s[2:3]
	v_mov_b32_e32 v2, 0x1000000
	v_mov_b32_e32 v3, s2
	global_atomic_add v2, v3, s[10:11] offset:768
